# conversion phase: small reused gain-vector loads back to the default policy (L1 hits); nt kept on the wide read-once loads
# speedup vs baseline: 1.0064x; 1.0064x over previous
.LBB0_699:
	s_cmpk_gt_i32 s51, 0x57f
	s_mov_b64 s[6:7], -1
	s_cbranch_scc0 .LBB0_809
	s_cmpk_gt_u32 s51, 0xaff
	s_cbranch_scc0 .LBB0_794
	s_cmpk_gt_u32 s51, 0x107f
	s_cbranch_scc0 .LBB0_791
	s_cmpk_gt_u32 s51, 0x15ff
	s_cbranch_scc0 .LBB0_776
	s_cmpk_gt_u32 s51, 0x1b7f
	s_cbranch_scc0 .LBB0_761
	s_cmpk_gt_u32 s51, 0x20ff
	s_cbranch_scc0 .LBB0_758
	s_cmpk_gt_u32 s51, 0x27ff
	s_cbranch_scc0 .LBB0_743
	s_cmpk_gt_u32 s51, 0x29ff
	s_cbranch_scc0 .LBB0_740
	s_cmpk_gt_u32 s51, 0x2bff
	s_cbranch_scc0 .LBB0_725
	s_cmpk_gt_u32 s51, 0x2dff
	s_cbranch_scc0 .LBB0_722
	s_add_i32 s18, s51, 0xffffd200
	s_bfe_u32 s36, s18, 0x10009
	v_readlane_b32 s0, v250, 3
	s_lshl_b32 s6, s36, 3
	v_readlane_b32 s1, v250, 4
	s_load_dwordx2 s[6:7], s[0:1], s6 offset:0x80
	s_and_b32 s90, s18, 0xfffffc00
	s_lshl_b64 s[18:19], s[90:91], 12
	v_readlane_b32 s68, v250, 48
	v_readlane_b32 s80, v250, 60
	s_waitcnt lgkmcnt(0)
	s_add_u32 s26, s6, s18
	s_addc_u32 s27, s7, s19
	s_lshl_b64 s[6:7], s[90:91], 2
	v_readlane_b32 s81, v250, 61
	s_add_u32 s18, s80, s6
	s_addc_u32 s19, s81, s7
	s_add_i32 s6, s49, 0x5c00
	s_and_b32 s37, s6, 0x3c0
	s_lshl_b32 s6, s51, 5
	s_and_b32 s52, s6, 0x3e0
	s_lshl_b32 s6, s52, 2
	s_add_u32 s6, s26, s6
	v_or_b32_e32 v36, s37, v0
	s_addc_u32 s7, s27, 0
	v_mov_b32_e32 v79, v181
	v_lshl_add_u64 v[4:5], s[6:7], 0, v[78:79]
	v_lshlrev_b32_e32 v180, 12, v36
	v_lshl_add_u64 v[4:5], v[4:5], 0, v[180:181]
	s_mov_b32 s6, 0x8000
	v_add_co_u32_e32 v6, vcc, s6, v4
	s_mov_b32 s0, 0x10000
	s_nop 0
	v_addc_co_u32_e32 v7, vcc, 0, v5, vcc
	global_load_dwordx4 v[28:31], v[4:5], off nt
	global_load_dwordx4 v[32:35], v[6:7], off nt
	v_add_co_u32_e32 v6, vcc, s0, v4
	s_mov_b32 s0, 0x18000
	s_nop 0
	v_addc_co_u32_e32 v7, vcc, 0, v5, vcc
	v_add_co_u32_e32 v8, vcc, s0, v4
	s_mov_b32 s6, 0x20000
	s_nop 0
	v_addc_co_u32_e32 v9, vcc, 0, v5, vcc
	global_load_dwordx4 v[20:23], v[6:7], off nt
	global_load_dwordx4 v[24:27], v[8:9], off nt
	v_add_co_u32_e32 v6, vcc, s6, v4
	v_readlane_b32 s0, v250, 46
	s_nop 0
	v_addc_co_u32_e32 v7, vcc, 0, v5, vcc
	v_add_co_u32_e32 v8, vcc, 0x28000, v4
	v_readlane_b32 s1, v250, 47
	s_nop 0
	v_addc_co_u32_e32 v9, vcc, 0, v5, vcc
	global_load_dwordx4 v[12:15], v[6:7], off nt
	global_load_dwordx4 v[16:19], v[8:9], off nt
	v_add_co_u32_e32 v6, vcc, 0x30000, v4
	v_cndmask_b32_e64 v37, 0, 1, s[0:1]
	s_nop 0
	v_addc_co_u32_e32 v7, vcc, 0, v5, vcc
	v_add_co_u32_e32 v8, vcc, 0x38000, v4
	v_cmp_ne_u32_e64 s[6:7], 1, v37
	s_nop 0
	v_addc_co_u32_e32 v9, vcc, 0, v5, vcc
	global_load_dwordx4 v[4:7], v[6:7], off nt
	s_nop 0
	global_load_dwordx4 v[8:11], v[8:9], off nt
	s_andn2_b64 vcc, exec, s[0:1]
	v_add_lshl_u32 v79, s37, v0, 2
	v_readlane_b32 s69, v250, 49
	v_readlane_b32 s70, v250, 50
	v_readlane_b32 s71, v250, 51
	v_readlane_b32 s72, v250, 52
	v_readlane_b32 s73, v250, 53
	v_readlane_b32 s74, v250, 54
	v_readlane_b32 s75, v250, 55
	v_readlane_b32 s76, v250, 56
	v_readlane_b32 s77, v250, 57
	v_readlane_b32 s78, v250, 58
	v_readlane_b32 s79, v250, 59
	v_readlane_b32 s82, v250, 62
	v_readlane_b32 s83, v250, 63
	s_cbranch_vccnz .LBB0_846
	v_lshlrev_b32_e32 v36, 2, v36
	global_load_dword v36, v36, s[18:19]
	s_nop 0
	global_load_dword v92, v79, s[18:19] offset:32
	s_waitcnt vmcnt(0)
	v_pk_mul_f32 v[80:81], v[30:31], v[36:37] op_sel_hi:[1,0]
	v_pk_mul_f32 v[82:83], v[28:29], v[36:37] op_sel_hi:[1,0]
	v_pk_mul_f32 v[38:39], v[34:35], v[92:93] op_sel_hi:[1,0]
	v_pk_mul_f32 v[36:37], v[32:33], v[92:93] op_sel_hi:[1,0]
	s_movk_i32 s1, 0xb1
	s_cbranch_execnz .LBB0_712

.LBB0_725:
	s_andn2_b64 vcc, exec, s[6:7]
	s_cbranch_vccnz .LBB0_739
	s_add_i32 s6, s49, 0x20800
	s_and_b32 s26, s6, 0x1ffc0
	s_lshl_b32 s6, s51, 5
	s_and_b32 s27, s6, 0x3e0
	v_or_b32_e32 v36, s26, v0
	s_lshl_b32 s90, s27, 2
	v_lshl_add_u64 v[4:5], v[60:61], 0, s[90:91]
	v_lshlrev_b32_e32 v180, 12, v36
	v_lshl_add_u64 v[4:5], v[4:5], 0, v[180:181]
	v_add_co_u32_e32 v6, vcc, 0x8000, v4
	s_mov_b32 s0, 0x10000
	s_nop 0
	v_addc_co_u32_e32 v7, vcc, 0, v5, vcc
	global_load_dwordx4 v[28:31], v[4:5], off nt
	global_load_dwordx4 v[32:35], v[6:7], off nt
	v_add_co_u32_e32 v6, vcc, s0, v4
	s_mov_b32 s0, 0x18000
	s_nop 0
	v_addc_co_u32_e32 v7, vcc, 0, v5, vcc
	v_add_co_u32_e32 v8, vcc, s0, v4
	v_readlane_b32 s18, v251, 0
	s_nop 0
	v_addc_co_u32_e32 v9, vcc, 0, v5, vcc
	global_load_dwordx4 v[20:23], v[6:7], off nt
	global_load_dwordx4 v[24:27], v[8:9], off nt
	v_add_co_u32_e32 v6, vcc, 0x20000, v4
	v_readlane_b32 s19, v251, 1
	s_nop 0
	v_addc_co_u32_e32 v7, vcc, 0, v5, vcc
	v_add_co_u32_e32 v8, vcc, 0x28000, v4
	v_cndmask_b32_e64 v37, 0, 1, s[18:19]
	s_nop 0
	v_addc_co_u32_e32 v9, vcc, 0, v5, vcc
	global_load_dwordx4 v[12:15], v[6:7], off nt
	global_load_dwordx4 v[16:19], v[8:9], off nt
	v_add_co_u32_e32 v6, vcc, 0x30000, v4
	v_cmp_ne_u32_e64 s[6:7], 1, v37
	s_nop 0
	v_addc_co_u32_e32 v7, vcc, 0, v5, vcc
	v_add_co_u32_e32 v8, vcc, 0x38000, v4
	v_add_lshl_u32 v79, s26, v0, 2
	s_nop 0
	v_addc_co_u32_e32 v9, vcc, 0, v5, vcc
	global_load_dwordx4 v[4:7], v[6:7], off nt
	s_nop 0
	global_load_dwordx4 v[8:11], v[8:9], off nt
	s_andn2_b64 vcc, exec, s[18:19]
	s_cbranch_vccnz .LBB0_842
	v_lshlrev_b32_e32 v36, 2, v36
	global_load_dword v36, v36, s[10:11]
	s_nop 0
	global_load_dword v92, v79, s[10:11] offset:32
	s_waitcnt vmcnt(0)
	v_pk_mul_f32 v[80:81], v[30:31], v[36:37] op_sel_hi:[1,0]
	v_pk_mul_f32 v[82:83], v[28:29], v[36:37] op_sel_hi:[1,0]
	v_pk_mul_f32 v[38:39], v[34:35], v[92:93] op_sel_hi:[1,0]
	v_pk_mul_f32 v[36:37], v[32:33], v[92:93] op_sel_hi:[1,0]
	s_cbranch_execnz .LBB0_729

.LBB0_743:
	s_andn2_b64 vcc, exec, s[6:7]
	s_cbranch_vccnz .LBB0_757
	s_add_i32 s6, s51, 0xdf00
	s_bfe_u32 s7, s6, 0xc0004
	s_mulk_i32 s7, 0x2493
	s_lshr_b32 s7, s7, 16
	s_mul_i32 s18, s7, 0x70
	s_sub_i32 s27, s6, s18
	s_lshl_b32 s6, s27, 7
	s_lshl_b32 s26, s7, 6
	s_and_b32 s90, s6, 0x3ff80
	v_or_b32_e32 v36, s26, v0
	v_lshl_add_u64 v[4:5], v[64:65], 0, s[90:91]
	s_movk_i32 s6, 0x3820
	v_mad_u64_u32 v[6:7], s[6:7], v36, s6, v[4:5]
	v_mul_u32_u24_e32 v180, 0x3820, v36
	v_lshl_add_u64 v[4:5], v[4:5], 0, v[180:181]
	s_mov_b32 s6, 0x1c000
	v_add_co_u32_e32 v8, vcc, s6, v4
	s_mov_b32 s6, 0x38000
	s_nop 0
	v_addc_co_u32_e32 v9, vcc, 0, v5, vcc
	global_load_dwordx4 v[28:31], v[6:7], off nt
	global_load_dwordx4 v[32:35], v[8:9], off offset:256 nt
	v_add_co_u32_e32 v6, vcc, s6, v4
	s_mov_b32 s6, 0x54000
	s_nop 0
	v_addc_co_u32_e32 v7, vcc, 0, v5, vcc
	v_add_co_u32_e32 v8, vcc, s6, v4
	s_mov_b32 s6, 0x70000
	s_nop 0
	v_addc_co_u32_e32 v9, vcc, 0, v5, vcc
	global_load_dwordx4 v[20:23], v[6:7], off offset:512 nt
	global_load_dwordx4 v[24:27], v[8:9], off offset:768 nt
	v_add_co_u32_e32 v6, vcc, s6, v4
	v_readlane_b32 s18, v251, 2
	s_nop 0
	v_addc_co_u32_e32 v7, vcc, 0, v5, vcc
	v_add_co_u32_e32 v8, vcc, 0x8c000, v4
	v_readlane_b32 s19, v251, 3
	s_nop 0
	v_addc_co_u32_e32 v9, vcc, 0, v5, vcc
	global_load_dwordx4 v[12:15], v[6:7], off offset:1024 nt
	global_load_dwordx4 v[16:19], v[8:9], off offset:1280 nt
	v_add_co_u32_e32 v6, vcc, 0xa8000, v4
	v_cndmask_b32_e64 v37, 0, 1, s[18:19]
	s_nop 0
	v_addc_co_u32_e32 v7, vcc, 0, v5, vcc
	v_add_co_u32_e32 v8, vcc, 0xc4000, v4
	v_cmp_ne_u32_e64 s[6:7], 1, v37
	s_nop 0
	v_addc_co_u32_e32 v9, vcc, 0, v5, vcc
	global_load_dwordx4 v[4:7], v[6:7], off offset:1536 nt
	s_nop 0
	global_load_dwordx4 v[8:11], v[8:9], off offset:1792 nt
	s_andn2_b64 vcc, exec, s[18:19]
	v_add_lshl_u32 v79, v0, s26, 2
	s_cbranch_vccnz .LBB0_838
	v_lshlrev_b32_e32 v36, 2, v36
	global_load_dword v36, v36, s[12:13]
	s_nop 0
	global_load_dword v92, v79, s[12:13] offset:32
	s_waitcnt vmcnt(0)
	v_pk_mul_f32 v[80:81], v[30:31], v[36:37] op_sel_hi:[1,0]
	v_pk_mul_f32 v[82:83], v[28:29], v[36:37] op_sel_hi:[1,0]
	v_pk_mul_f32 v[38:39], v[34:35], v[92:93] op_sel_hi:[1,0]
	v_pk_mul_f32 v[36:37], v[32:33], v[92:93] op_sel_hi:[1,0]
	s_cbranch_execnz .LBB0_747

.LBB0_761:
	s_andn2_b64 vcc, exec, s[6:7]
	s_cbranch_vccnz .LBB0_775
	s_add_i32 s6, s51, 0xea00
	s_and_b32 s7, s6, 0xffff
	s_mul_i32 s7, s7, 0xba2f
	s_lshr_b32 s18, s7, 16
	s_lshr_b32 s7, s7, 22
	s_mulk_i32 s7, 0x58
	s_sub_i32 s6, s6, s7
	s_and_b32 s27, s6, 0xffff
	s_and_b32 s26, s18, 0xffc0
	v_or_b32_e32 v36, s26, v0
	s_lshl_b32 s90, s27, 7
	v_lshl_add_u64 v[4:5], v[68:69], 0, s[90:91]
	v_mul_u32_u24_e32 v180, 0x2c00, v36
	v_mad_u64_u32 v[6:7], s[6:7], v36, s66, v[4:5]
	v_lshl_add_u64 v[4:5], v[4:5], 0, v[180:181]
	s_mov_b32 s0, 0x16000
	v_add_co_u32_e32 v8, vcc, s0, v4
	s_mov_b32 s0, 0x2c000
	s_nop 0
	v_addc_co_u32_e32 v9, vcc, 0, v5, vcc
	global_load_dwordx4 v[28:31], v[6:7], off nt
	global_load_dwordx4 v[32:35], v[8:9], off nt
	v_add_co_u32_e32 v6, vcc, s0, v4
	s_mov_b32 s0, 0x42000
	s_nop 0
	v_addc_co_u32_e32 v7, vcc, 0, v5, vcc
	v_add_co_u32_e32 v8, vcc, s0, v4
	s_mov_b32 s0, 0x58000
	s_nop 0
	v_addc_co_u32_e32 v9, vcc, 0, v5, vcc
	global_load_dwordx4 v[20:23], v[6:7], off nt
	global_load_dwordx4 v[24:27], v[8:9], off nt
	v_add_co_u32_e32 v6, vcc, s0, v4
	v_readlane_b32 s18, v251, 20
	s_nop 0
	v_addc_co_u32_e32 v7, vcc, 0, v5, vcc
	v_add_co_u32_e32 v8, vcc, 0x6e000, v4
	v_readlane_b32 s19, v251, 21
	s_nop 0
	v_addc_co_u32_e32 v9, vcc, 0, v5, vcc
	global_load_dwordx4 v[12:15], v[6:7], off nt
	global_load_dwordx4 v[16:19], v[8:9], off nt
	v_add_co_u32_e32 v6, vcc, 0x84000, v4
	v_cndmask_b32_e64 v37, 0, 1, s[18:19]
	s_nop 0
	v_addc_co_u32_e32 v7, vcc, 0, v5, vcc
	v_add_co_u32_e32 v8, vcc, 0x9a000, v4
	v_cmp_ne_u32_e64 s[6:7], 1, v37
	s_nop 0
	v_addc_co_u32_e32 v9, vcc, 0, v5, vcc
	global_load_dwordx4 v[4:7], v[6:7], off nt
	s_nop 0
	global_load_dwordx4 v[8:11], v[8:9], off nt
	s_andn2_b64 vcc, exec, s[18:19]
	v_add_lshl_u32 v79, v0, s26, 2
	s_cbranch_vccnz .LBB0_834
	v_lshlrev_b32_e32 v36, 2, v36
	global_load_dword v36, v36, s[14:15]
	s_nop 0
	global_load_dword v92, v79, s[14:15] offset:32
	s_waitcnt vmcnt(0)
	v_pk_mul_f32 v[80:81], v[30:31], v[36:37] op_sel_hi:[1,0]
	v_pk_mul_f32 v[82:83], v[28:29], v[36:37] op_sel_hi:[1,0]
	v_pk_mul_f32 v[38:39], v[34:35], v[92:93] op_sel_hi:[1,0]
	v_pk_mul_f32 v[36:37], v[32:33], v[92:93] op_sel_hi:[1,0]
	s_cbranch_execnz .LBB0_765

.LBB0_776:
	s_andn2_b64 vcc, exec, s[6:7]
	s_cbranch_vccnz .LBB0_790
	s_add_i32 s6, s51, 0xef80
	s_and_b32 s7, s6, 0xffff
	s_mul_i32 s7, s7, 0xba2f
	s_lshr_b32 s18, s7, 16
	s_lshr_b32 s7, s7, 22
	s_mulk_i32 s7, 0x58
	s_sub_i32 s6, s6, s7
	s_and_b32 s27, s6, 0xffff
	s_and_b32 s26, s18, 0xffc0
	v_or_b32_e32 v36, s26, v0
	s_lshl_b32 s90, s27, 7
	v_lshl_add_u64 v[4:5], v[70:71], 0, s[90:91]
	v_mul_u32_u24_e32 v180, 0x2c00, v36
	v_mad_u64_u32 v[6:7], s[6:7], v36, s66, v[4:5]
	v_lshl_add_u64 v[4:5], v[4:5], 0, v[180:181]
	s_mov_b32 s0, 0x16000
	v_add_co_u32_e32 v8, vcc, s0, v4
	s_mov_b32 s0, 0x2c000
	s_nop 0
	v_addc_co_u32_e32 v9, vcc, 0, v5, vcc
	global_load_dwordx4 v[28:31], v[6:7], off nt
	global_load_dwordx4 v[32:35], v[8:9], off nt
	v_add_co_u32_e32 v6, vcc, s0, v4
	s_mov_b32 s0, 0x42000
	s_nop 0
	v_addc_co_u32_e32 v7, vcc, 0, v5, vcc
	v_add_co_u32_e32 v8, vcc, s0, v4
	s_mov_b32 s0, 0x58000
	s_nop 0
	v_addc_co_u32_e32 v9, vcc, 0, v5, vcc
	global_load_dwordx4 v[20:23], v[6:7], off nt
	global_load_dwordx4 v[24:27], v[8:9], off nt
	v_add_co_u32_e32 v6, vcc, s0, v4
	v_readlane_b32 s18, v251, 20
	s_nop 0
	v_addc_co_u32_e32 v7, vcc, 0, v5, vcc
	v_add_co_u32_e32 v8, vcc, 0x6e000, v4
	v_readlane_b32 s19, v251, 21
	s_nop 0
	v_addc_co_u32_e32 v9, vcc, 0, v5, vcc
	global_load_dwordx4 v[12:15], v[6:7], off nt
	global_load_dwordx4 v[16:19], v[8:9], off nt
	v_add_co_u32_e32 v6, vcc, 0x84000, v4
	v_cndmask_b32_e64 v37, 0, 1, s[18:19]
	s_nop 0
	v_addc_co_u32_e32 v7, vcc, 0, v5, vcc
	v_add_co_u32_e32 v8, vcc, 0x9a000, v4
	v_cmp_ne_u32_e64 s[6:7], 1, v37
	s_nop 0
	v_addc_co_u32_e32 v9, vcc, 0, v5, vcc
	global_load_dwordx4 v[4:7], v[6:7], off nt
	s_nop 0
	global_load_dwordx4 v[8:11], v[8:9], off nt
	s_andn2_b64 vcc, exec, s[18:19]
	v_add_lshl_u32 v79, v0, s26, 2
	s_cbranch_vccnz .LBB0_830
	v_lshlrev_b32_e32 v36, 2, v36
	global_load_dword v36, v36, s[14:15]
	s_nop 0
	global_load_dword v92, v79, s[14:15] offset:32
	s_waitcnt vmcnt(0)
	v_pk_mul_f32 v[80:81], v[30:31], v[36:37] op_sel_hi:[1,0]
	v_pk_mul_f32 v[82:83], v[28:29], v[36:37] op_sel_hi:[1,0]
	v_pk_mul_f32 v[38:39], v[34:35], v[92:93] op_sel_hi:[1,0]
	v_pk_mul_f32 v[36:37], v[32:33], v[92:93] op_sel_hi:[1,0]
	s_cbranch_execnz .LBB0_780

.LBB0_794:
	s_andn2_b64 vcc, exec, s[6:7]
	s_cbranch_vccnz .LBB0_808
	s_add_i32 s6, s51, 0xfa80
	s_and_b32 s7, s6, 0xffff
	s_mul_i32 s7, s7, 0xba2f
	s_lshr_b32 s18, s7, 16
	s_lshr_b32 s7, s7, 22
	s_mulk_i32 s7, 0x58
	s_sub_i32 s6, s6, s7
	s_and_b32 s27, s6, 0xffff
	s_and_b32 s26, s18, 0xffc0
	v_or_b32_e32 v36, s26, v0
	s_lshl_b32 s90, s27, 7
	v_lshl_add_u64 v[4:5], v[74:75], 0, s[90:91]
	v_mul_u32_u24_e32 v180, 0x2c00, v36
	v_mad_u64_u32 v[6:7], s[6:7], v36, s66, v[4:5]
	v_lshl_add_u64 v[4:5], v[4:5], 0, v[180:181]
	s_mov_b32 s0, 0x16000
	v_add_co_u32_e32 v8, vcc, s0, v4
	s_mov_b32 s0, 0x2c000
	s_nop 0
	v_addc_co_u32_e32 v9, vcc, 0, v5, vcc
	global_load_dwordx4 v[28:31], v[6:7], off nt
	global_load_dwordx4 v[32:35], v[8:9], off nt
	v_add_co_u32_e32 v6, vcc, s0, v4
	s_mov_b32 s0, 0x42000
	s_nop 0
	v_addc_co_u32_e32 v7, vcc, 0, v5, vcc
	v_add_co_u32_e32 v8, vcc, s0, v4
	s_mov_b32 s0, 0x58000
	s_nop 0
	v_addc_co_u32_e32 v9, vcc, 0, v5, vcc
	global_load_dwordx4 v[20:23], v[6:7], off nt
	global_load_dwordx4 v[24:27], v[8:9], off nt
	v_add_co_u32_e32 v6, vcc, s0, v4
	v_cndmask_b32_e64 v37, 0, 1, s[30:31]
	s_nop 0
	v_addc_co_u32_e32 v7, vcc, 0, v5, vcc
	v_add_co_u32_e32 v8, vcc, 0x6e000, v4
	v_cmp_ne_u32_e64 s[6:7], 1, v37
	s_nop 0
	v_addc_co_u32_e32 v9, vcc, 0, v5, vcc
	global_load_dwordx4 v[12:15], v[6:7], off nt
	global_load_dwordx4 v[16:19], v[8:9], off nt
	v_add_co_u32_e32 v6, vcc, 0x84000, v4
	v_add_lshl_u32 v79, v0, s26, 2
	s_nop 0
	v_addc_co_u32_e32 v7, vcc, 0, v5, vcc
	v_add_co_u32_e32 v8, vcc, 0x9a000, v4
	s_nop 1
	v_addc_co_u32_e32 v9, vcc, 0, v5, vcc
	global_load_dwordx4 v[4:7], v[6:7], off nt
	s_nop 0
	global_load_dwordx4 v[8:11], v[8:9], off nt
	s_andn2_b64 vcc, exec, s[30:31]
	s_cbranch_vccnz .LBB0_826
	v_lshlrev_b32_e32 v36, 2, v36
	global_load_dword v36, v36, s[16:17]
	s_nop 0
	global_load_dword v92, v79, s[16:17] offset:32
	s_waitcnt vmcnt(0)
	v_pk_mul_f32 v[80:81], v[30:31], v[36:37] op_sel_hi:[1,0]
	v_pk_mul_f32 v[82:83], v[28:29], v[36:37] op_sel_hi:[1,0]
	v_pk_mul_f32 v[38:39], v[34:35], v[92:93] op_sel_hi:[1,0]
	v_pk_mul_f32 v[36:37], v[32:33], v[92:93] op_sel_hi:[1,0]
	s_cbranch_execnz .LBB0_798

.LBB0_809:
	s_andn2_b64 vcc, exec, s[6:7]
	s_cbranch_vccnz .LBB0_698
	s_mul_hi_i32 s6, s51, 0x2e8ba2e9
	s_lshr_b32 s7, s6, 31
	s_ashr_i32 s52, s6, 4
	s_add_i32 s52, s52, s7
	s_mul_i32 s6, s52, 0xfffff500
	s_add_i32 s26, s45, s6
	s_lshl_b32 s18, s52, 6
	v_or_b32_e32 v36, s18, v0
	s_ashr_i32 s27, s26, 31
	v_lshl_add_u64 v[4:5], s[26:27], 2, v[76:77]
	v_or_b32_e32 v8, 8, v36
	v_mad_i64_i32 v[6:7], s[6:7], v36, s66, v[4:5]
	v_mad_i64_i32 v[8:9], s[6:7], v8, s66, v[4:5]
	global_load_dwordx4 v[28:31], v[6:7], off nt
	global_load_dwordx4 v[32:35], v[8:9], off nt
	v_or_b32_e32 v6, 16, v36
	v_or_b32_e32 v8, 24, v36
	v_mad_i64_i32 v[6:7], s[6:7], v6, s66, v[4:5]
	v_mad_i64_i32 v[8:9], s[6:7], v8, s66, v[4:5]
	global_load_dwordx4 v[20:23], v[6:7], off nt
	global_load_dwordx4 v[24:27], v[8:9], off nt
	v_or_b32_e32 v6, 32, v36
	v_or_b32_e32 v8, 40, v36
	v_mad_i64_i32 v[6:7], s[6:7], v6, s66, v[4:5]
	v_mad_i64_i32 v[8:9], s[6:7], v8, s66, v[4:5]
	global_load_dwordx4 v[12:15], v[6:7], off nt
	global_load_dwordx4 v[16:19], v[8:9], off nt
	v_or_b32_e32 v6, 48, v36
	v_or_b32_e32 v8, 56, v36
	v_mad_i64_i32 v[6:7], s[6:7], v6, s66, v[4:5]
	v_mad_i64_i32 v[8:9], s[6:7], v8, s66, v[4:5]
	global_load_dwordx4 v[4:7], v[6:7], off nt
	s_nop 0
	global_load_dwordx4 v[8:11], v[8:9], off nt
	v_cndmask_b32_e64 v37, 0, 1, s[30:31]
	v_cmp_ne_u32_e64 s[6:7], 1, v37
	s_andn2_b64 vcc, exec, s[30:31]
	s_cbranch_vccnz .LBB0_821
	s_ashr_i32 s19, s18, 31
	v_ashrrev_i32_e32 v37, 31, v36
	v_lshl_add_u64 v[38:39], s[18:19], 0, v[0:1]
	v_lshl_add_u64 v[36:37], v[36:37], 2, s[16:17]
	v_lshl_add_u64 v[38:39], v[38:39], 2, s[16:17]
	global_load_dword v36, v[36:37], off
	s_nop 0
	global_load_dword v92, v[38:39], off offset:32
	s_waitcnt vmcnt(0)
	v_pk_mul_f32 v[80:81], v[30:31], v[36:37] op_sel_hi:[1,0]
	v_pk_mul_f32 v[82:83], v[28:29], v[36:37] op_sel_hi:[1,0]
	v_pk_mul_f32 v[38:39], v[34:35], v[92:93] op_sel_hi:[1,0]
	v_pk_mul_f32 v[36:37], v[32:33], v[92:93] op_sel_hi:[1,0]
	s_cbranch_execnz .LBB0_813

.LBB0_865:
	v_bfe_u32 v1, v0, 9, 4
	v_cmp_gt_u32_e32 vcc, 8, v1
	v_mov_b32_e32 v6, 0
	s_and_saveexec_b64 s[10:11], vcc
	s_cbranch_execz .LBB0_864
	v_readlane_b32 s68, v251, 22
	v_and_b32_e32 v8, 0x3fe, v3
	v_ashrrev_i32_e32 v10, 13, v0
	v_readlane_b32 s82, v251, 36
	v_readlane_b32 s83, v251, 37
	v_lshl_or_b32 v6, v10, 10, v8
	v_mul_u32_u24_e32 v11, 0xe08, v8
	v_mov_b64_e32 v[8:9], s[82:83]
	s_mov_b32 s12, 0xe08000
	v_mad_i64_i32 v[8:9], s[12:13], v10, s12, v[8:9]
	v_lshlrev_b32_e32 v180, 2, v11
	v_lshl_add_u64 v[8:9], v[8:9], 0, v[180:181]
	v_lshlrev_b32_e32 v180, 2, v1
	v_lshl_add_u64 v[8:9], v[8:9], 0, v[180:181]
	v_add_co_u32_e32 v10, vcc, 0x3000, v8
	v_ashrrev_i32_e32 v7, 31, v6
	v_readlane_b32 s80, v251, 34
	v_readlane_b32 s81, v251, 35
	v_addc_co_u32_e32 v11, vcc, 0, v9, vcc
	s_nop 0
	v_lshl_add_u64 v[6:7], v[6:7], 2, s[80:81]
	v_add_co_u32_e32 v8, vcc, 0x7000, v8
	global_load_dwordx2 v[6:7], v[6:7], off nt
	s_nop 0
	v_addc_co_u32_e32 v9, vcc, 0, v9, vcc
	global_load_dword v10, v[10:11], off offset:2048
	s_nop 0
	global_load_dword v11, v[8:9], off offset:32
	v_readlane_b32 s69, v251, 23
	v_readlane_b32 s70, v251, 24
	v_readlane_b32 s71, v251, 25
	v_readlane_b32 s72, v251, 26
	v_readlane_b32 s73, v251, 27
	v_readlane_b32 s74, v251, 28
	v_readlane_b32 s75, v251, 29
	v_readlane_b32 s76, v251, 30
	v_readlane_b32 s77, v251, 31
	v_readlane_b32 s78, v251, 32
	v_readlane_b32 s79, v251, 33
	s_waitcnt vmcnt(0)
	v_pk_mul_f32 v[6:7], v[6:7], v[10:11]
	s_nop 0
	v_cvt_pk_bf16_f32 v6, v6, v7
	s_branch .LBB0_864
